# attention: drop spurious vmcnt(0) after step-0 DMA issue (L0); skip redundant T5 bias-table rebuild in diff-attn component 1 (table from component 0 persists in LDS)
# baseline (speedup 1.0000x reference)
; #define WAIT_BAR(N) asm volatile("s_waitcnt vmcnt(" #N ") lgkmcnt(0)\n\ts_barrier":::"memory")
;   #define DMA_K(t,slot) glds16s(Kb+(long)(t)*KVBLK*kp,ksrc,(unsigned)__builtin_amdgcn_readfirstlane(kdst+(slot)))
;   #define DMA_V(t,slot) do{ glds16s(Vb+(long)(t)*KVBLK*vp,vsrc,(unsigned)__builtin_amdgcn_readfirstlane(vdst+(slot))); \
;       if(VH==2) glds16s(Vb+(long)(t)*KVBLK*vp+64,vsrc,(unsigned)__builtin_amdgcn_readfirstlane(vdst+(slot)+8192)); }while(0)
;   #define BIASADD(P0,P1,t) do{ if(HAS_BIAS&&(t)>=tn0&&(t)<tn1){ const lds_f32*bp_=btab+(64*(t)+lanebias); \
;     _Pragma("unroll") for(int r=0;r<16;++r){ P0[r]+=bp_[(r&3)+8*(r>>2)]; P1[r]+=bp_[(r&3)+8*(r>>2)+32]; } } }while(0)
;   #define ROT() do{sv_prev=sv_cur;sv_cur=sv_next;sv_next=(sv_next==2*VSL)?0:sv_next+VSL;}while(0)
;   #define KPRE(tn) do{ const lds_cptr kn_=kp0+(((tn)&3)*KSL); kf[0]=KLD(kn_); kf[1]=KLD(kn_+512); kf[2]=KLD(kn_+2048); kf[3]=KLD(kn_+2560); }while(0)
; template<int VH,bool HAS_BIAS,int MODE> __device__ __forceinline__ void attn_unit2(const bf16*Qb,int qp,const bf16*__restrict__ Kb,int kp,const bf16*__restrict__ Vb,int vp,bf16*Ob,int op,int q0,int NT,const float*relb,char*shm,float lam,const float*subg,float gmul){
;     ...
;   DMA_K(0,0);DMA_V(0,0);DMA_K(1,KSL);
;   bf16x8 qr[4];
;   #pragma unroll
;   for(int d0=0;d0<4;++d0)qr[d0]=*reinterpret_cast<const bf16x8*>(&Qw[(long)r32*qp+d0*16+hi*8]);
;   DMA_K(2,2*KSL);
;   float l_reg=0.f;f32x16 o[2*VH];
;   #pragma unroll
;   for(int d_=0;d_<2*VH;++d_)o[d_]=f32x16{};
;   const f32x16 zero16=f32x16{};
;   f32x16 pA0,pA1,pB0,pB1; bf16x8 kf[4];
;   int sv_prev=0,sv_cur=0,sv_next=VSL;
;     ...
;   if(VH==1){WAIT_BAR(3);}else{WAIT_BAR(4);}
;   qkt(pA0,pA1,shm+LM::L_K,qr,zero16,r32,hi);
;   BIASADD(pA0,pA1,0);
;   _Pragma("unroll") for(int r=0;r<16;++r){pA0[r]=__builtin_amdgcn_exp2f(pA0[r]);pA1[r]=__builtin_amdgcn_exp2f(pA1[r]);}
;   WAIT_BAR(0);
;   DMA_K(3,3*KSL);DMA_V(1,VSL);
;   ROT();
;   KPRE(1);
.LBB0_614:
	s_lshl_b64 s[10:11], s[6:7], 10
	s_lshl_b64 s[8:9], s[6:7], 11
	s_add_u32 s4, s38, s8
	s_addc_u32 s14, s39, s9
	s_lshl_b32 s8, s13, 6
	s_ashr_i32 s9, s8, 31
	s_lshl_b64 s[8:9], s[8:9], 1
	s_add_u32 s15, s4, s8
	s_addc_u32 s14, s14, s9
	s_lshl_b64 s[6:7], s[6:7], 9
	s_add_u32 s4, s33, s6
	s_addc_u32 s13, s46, s7
	s_lshl_b32 s20, s12, 7
	s_add_u32 s12, s4, s20
	s_addc_u32 s13, s13, 0
	s_add_u32 s4, s47, s6
	s_addc_u32 s6, s48, s7
	v_mov_b32_e32 v44, v182
	s_add_u32 s20, s4, s20
	s_addc_u32 s21, s6, 0
	v_readfirstlane_b32 s52, v44
	s_ashr_i32 s4, s52, 6
	s_lshl_b32 s6, s22, 8
	s_lshl_b32 s7, s4, 5
	s_add_i32 s6, s7, s6
	s_ashr_i32 s7, s6, 31
	s_lshl_b64 s[6:7], s[6:7], 11
	s_add_u32 s22, s15, s6
	v_and_b32_e32 v158, 63, v44
	s_addc_u32 s23, s14, s7
	s_lshl_b32 s14, s4, 4
	v_bfe_u32 v0, v44, 2, 4
	v_lshl_add_u32 v169, v158, 9, s14
	v_and_or_b32 v0, s14, 48, v0
	s_ashr_i32 s14, s52, 3
	s_and_b32 s14, s14, 0x7fffffe0
	s_lshl_b32 s54, s4, 10
	s_cmp_lg_u32 0, -1
	v_lshl_add_u32 v0, v0, 8, s14
	v_lshlrev_b32_e32 v160, 3, v44
	s_cselect_b32 s14, 0, 0
	v_and_b32_e32 v165, 24, v160
	s_add_i32 s54, s54, s14
	v_and_b32_e32 v161, 31, v44
	v_or_b32_e32 v0, v0, v165
	s_add_i32 s55, s54, 0x8000
	s_mov_b32 s14, m0
	s_mov_b32 m0, s54
	s_nop 0
	global_load_lds_dwordx4 v169, s[12:13]
	s_mov_b32 m0, s14
	v_bfe_u32 v162, v44, 5, 1
	v_lshlrev_b32_e32 v170, 1, v0
	s_mov_b32 s14, m0
	s_mov_b32 m0, s55
	s_nop 0
	global_load_lds_dwordx4 v170, s[20:21]
	s_mov_b32 m0, s14
	s_add_u32 s34, s12, 0x8000
	v_lshlrev_b32_e32 v0, 11, v161
	s_addc_u32 s35, s13, 0
	s_add_i32 s14, s54, 0x2000
	s_mov_b32 s15, m0
	s_mov_b32 m0, s14
	s_nop 0
	global_load_lds_dwordx4 v169, s[34:35]
	s_mov_b32 m0, s15
	v_lshl_or_b32 v0, v162, 4, v0
	global_load_dwordx4 v[124:127], v0, s[22:23]
	global_load_dwordx4 v[120:123], v0, s[22:23] offset:32
	global_load_dwordx4 v[116:119], v0, s[22:23] offset:64
	global_load_dwordx4 v[112:115], v0, s[22:23] offset:96
	s_add_u32 s22, s12, 0x10000
	v_lshlrev_b32_e32 v0, 10, v162
	v_lshlrev_b32_e32 v1, 4, v161
	s_addc_u32 s23, s13, 0
	s_add_i32 s14, s54, 0x4000
	s_mov_b32 s15, m0
	s_mov_b32 m0, s14
	s_nop 0
	global_load_lds_dwordx4 v169, s[22:23]
	s_mov_b32 m0, s15
	v_add3_u32 v164, 0, v0, v1
	s_waitcnt vmcnt(3) lgkmcnt(0)
	s_barrier
	ds_read_b128 v[0:3], v164
	ds_read_b128 v[16:19], v164 offset:512
	ds_read_b128 v[32:35], v164 offset:2048
	s_add_u32 s22, s12, 0x18000
	s_addc_u32 s23, s13, 0
	s_add_i32 s14, s54, 0x6000
	s_add_u32 s34, s20, 0x8000
	s_addc_u32 s35, s21, 0
	s_add_i32 s61, s53, -5
	v_mov_b32_e32 v168, 0
	s_mov_b32 s57, 1
	s_mov_b32 s65, 5
	s_mov_b32 s64, 0
	s_mov_b32 s66, 0x8000
	s_movk_i32 s56, 0x2000
	s_mov_b64 s[44:45], 0x10000
	s_movk_i32 s63, 0x4000
	s_movk_i32 s60, 0x4000
	s_waitcnt vmcnt(3) lgkmcnt(2)
	v_mfma_f32_32x32x16_bf16 v[0:15], v[0:3], v[124:127], 0
	s_waitcnt vmcnt(2) lgkmcnt(0)
	v_mfma_f32_32x32x16_bf16 v[0:15], v[32:35], v[120:123], v[0:15]
	ds_read_b128 v[32:35], v164 offset:2560
	ds_read_b128 v[36:39], v164 offset:4608
	ds_read_b128 v[40:43], v164 offset:4096
	v_mfma_f32_32x32x16_bf16 v[16:31], v[16:19], v[124:127], 0
	s_waitcnt lgkmcnt(2)
	v_mfma_f32_32x32x16_bf16 v[16:31], v[32:35], v[120:123], v[16:31]
	v_lshlrev_b32_e32 v32, 1, v44
	v_lshlrev_b32_e32 v33, 4, v44
	v_and_b32_e32 v166, 32, v32
	v_and_b32_e32 v32, 0xc0, v33
	v_lshl_or_b32 v163, v162, 8, v32
	v_add_u32_e32 v32, 0, v166
	v_add3_u32 v167, v32, v165, v163
	s_waitcnt vmcnt(1) lgkmcnt(0)
	v_mfma_f32_32x32x16_bf16 v[0:15], v[40:43], v[116:119], v[0:15]
	ds_read_b128 v[32:35], v164 offset:6656
	ds_read_b128 v[40:43], v164 offset:6144
	s_waitcnt vmcnt(0) lgkmcnt(0)
	s_barrier
	s_mov_b32 s15, m0
	s_mov_b32 m0, s14
	s_nop 0
	global_load_lds_dwordx4 v169, s[22:23]
	s_mov_b32 m0, s15
	s_add_i32 s14, s54, 0xa000
	s_mov_b32 s15, m0
	s_mov_b32 m0, s14
	s_nop 0
	global_load_lds_dwordx4 v170, s[34:35]
	s_mov_b32 m0, s15
	ds_read_b128 v[128:131], v164 offset:10752
	ds_read_b128 v[132:135], v164 offset:10240
	ds_read_b128 v[136:139], v164 offset:8704
	ds_read_b128 v[80:83], v164 offset:8192
	s_add_u32 s40, s20, 0x18000
	v_mfma_f32_32x32x16_bf16 v[16:31], v[36:39], v[116:119], v[16:31]
	s_addc_u32 s41, s21, 0
	s_add_u32 s42, s12, 0x28000
	s_addc_u32 s43, s13, 0
	s_waitcnt lgkmcnt(4)
	v_mfma_f32_32x32x16_bf16 v[0:15], v[40:43], v[112:115], v[0:15]
	v_mfma_f32_32x32x16_bf16 v[16:31], v[32:35], v[112:115], v[16:31]
	s_nop 10
	v_exp_f32_e32 v48, v0
	v_exp_f32_e32 v49, v1
	v_exp_f32_e32 v50, v2
	v_exp_f32_e32 v51, v3
	v_exp_f32_e32 v52, v4
	v_exp_f32_e32 v53, v5
	v_exp_f32_e32 v54, v6
	v_exp_f32_e32 v32, v16
	v_exp_f32_e32 v33, v17
	v_exp_f32_e32 v34, v18
	v_exp_f32_e32 v35, v19
	v_exp_f32_e32 v36, v20
	v_exp_f32_e32 v37, v21
	v_exp_f32_e32 v38, v22
	v_exp_f32_e32 v39, v23
	v_exp_f32_e32 v40, v24
	v_exp_f32_e32 v41, v25
	v_exp_f32_e32 v42, v26
	v_exp_f32_e32 v43, v27
	v_exp_f32_e32 v44, v28
	v_exp_f32_e32 v45, v29
	v_exp_f32_e32 v46, v30
	v_exp_f32_e32 v47, v31
	v_exp_f32_e32 v55, v7
	v_exp_f32_e32 v56, v8
	v_exp_f32_e32 v57, v9
	v_exp_f32_e32 v58, v10
	v_exp_f32_e32 v59, v11
	v_exp_f32_e32 v60, v12
	v_exp_f32_e32 v61, v13
	v_exp_f32_e32 v62, v14
	v_exp_f32_e32 v63, v15
	v_mov_b32_e32 v0, 0
	v_mov_b32_e32 v1, v168
	v_mov_b32_e32 v2, v168
	v_mov_b32_e32 v3, v168
	v_mov_b32_e32 v4, v168
	v_mov_b32_e32 v5, v168
	v_mov_b32_e32 v6, v168
	v_mov_b32_e32 v7, v168
	v_mov_b32_e32 v8, v168
	v_mov_b32_e32 v9, v168
	v_mov_b32_e32 v10, v168
	v_mov_b32_e32 v11, v168
	v_mov_b32_e32 v12, v168
	v_mov_b32_e32 v13, v168
	v_mov_b32_e32 v14, v168
	v_mov_b32_e32 v15, v168
	v_mov_b32_e32 v16, 0
	v_mov_b32_e32 v17, v168
	v_mov_b32_e32 v18, v168
	v_mov_b32_e32 v19, v168
	v_mov_b32_e32 v20, v168
	v_mov_b32_e32 v21, v168
	v_mov_b32_e32 v22, v168
	v_mov_b32_e32 v23, v168
	v_mov_b32_e32 v24, v168
	v_mov_b32_e32 v25, v168
	v_mov_b32_e32 v26, v168
	v_mov_b32_e32 v27, v168
	v_mov_b32_e32 v28, v168
	v_mov_b32_e32 v29, v168
	v_mov_b32_e32 v30, v168
	v_mov_b32_e32 v31, v168

; #define SBAR() __builtin_amdgcn_sched_barrier(0)
;   #define PKW(P,B) cvtpk_s(P[B],P[B+1])
; template<int VH,bool HAS_BIAS,int MODE> __device__ __forceinline__ void attn_unit2(const bf16*Qb,int qp,const bf16*__restrict__ Kb,int kp,const bf16*__restrict__ Vb,int vp,bf16*Ob,int op,int q0,int NT,const float*relb,char*shm,float lam,const float*subg,float gmul){
;     ...
;   { float sacc=pB0[0]+pB0[1]; _Pragma("unroll") for(int r=2;r<16;++r)sacc+=pB0[r]; _Pragma("unroll") for(int r=0;r<16;++r)sacc+=pB1[r]; l_reg+=sacc;
;     pw0=(u32x4){PKW(pB0,0),PKW(pB0,2),PKW(pB0,4),PKW(pB0,6)};pw1=(u32x4){PKW(pB0,8),PKW(pB0,10),PKW(pB0,12),PKW(pB0,14)};pw2=(u32x4){PKW(pB1,0),PKW(pB1,2),PKW(pB1,4),PKW(pB1,6)};pw3=(u32x4){PKW(pB1,8),PKW(pB1,10),PKW(pB1,12),PKW(pB1,14)};
;     SBAR(); pv(o,vb0+sv_cur,PAF(0),PAF(1),PAF(2),PAF(3)); if(VH==2){ SBAR(); pv(o+2*(VH-1),vb0+sv_cur+8192,PAF(0),PAF(1),PAF(2),PAF(3)); } }
;     ...
;   {auto rr=__builtin_amdgcn_permlane32_swap(__float_as_uint(l_reg),__float_as_uint(l_reg),false,false);l_reg=__uint_as_float(rr[0])+__uint_as_float(rr[1]);}
;   if(hi==0)wsf[32+r32]=l_reg;
;   asm volatile("s_waitcnt lgkmcnt(0)\n\ts_barrier":::"memory");
.LBB0_1139:
	v_add_f32_e32 v66, v98, v99
	v_add_f32_e32 v66, v100, v66
	v_add_f32_e32 v66, v101, v66
	v_add_f32_e32 v66, v102, v66
	v_add_f32_e32 v66, v103, v66
	v_add_f32_e32 v66, v104, v66
	v_add_f32_e32 v66, v105, v66
	v_add_f32_e32 v66, v106, v66
	v_add_f32_e32 v66, v107, v66
	v_add_f32_e32 v66, v108, v66
	v_add_f32_e32 v66, v109, v66
	v_add_f32_e32 v66, v110, v66
	v_add_f32_e32 v66, v111, v66
	v_add_f32_e32 v66, v112, v66
	v_add_f32_e32 v66, v113, v66
	v_add_f32_e32 v66, v66, v114
	v_add_f32_e32 v66, v115, v66
	v_add_f32_e32 v66, v116, v66
	v_add_f32_e32 v66, v117, v66
	v_add_f32_e32 v66, v118, v66
	v_add_f32_e32 v66, v119, v66
	v_add_f32_e32 v66, v120, v66
	v_add_f32_e32 v66, v121, v66
	v_add_f32_e32 v66, v122, v66
	v_add_f32_e32 v66, v123, v66
	s_and_b32 s6, s56, 0x3fffffc0
	v_add_f32_e32 v66, v124, v66
	s_lshl_b32 s6, s6, 2
	v_add_f32_e32 v66, v125, v66
	s_add_i32 s8, s6, 0
	v_add_f32_e32 v66, v126, v66
	s_add_i32 s8, s8, 0x14000
	v_add_f32_e32 v66, v127, v66
	s_cmp_lg_u32 0, -1
	v_add_f32_e32 v66, v128, v66
	s_cselect_b32 s6, 0, 0
	v_add_f32_e32 v66, v129, v66
	s_add_i32 s6, s6, 0x8000
	v_add_f32_e32 v0, v66, v0
	v_cvt_pk_bf16_f32 v66, v98, v99
	v_add3_u32 v82, v197, s6, v195
	v_cvt_pk_bf16_f32 v67, v100, v101
	v_cvt_pk_bf16_f32 v68, v102, v103
	v_cvt_pk_bf16_f32 v69, v104, v105
	v_cvt_pk_bf16_f32 v70, v106, v107
	v_cvt_pk_bf16_f32 v71, v108, v109
	v_cvt_pk_bf16_f32 v72, v110, v111
	v_cvt_pk_bf16_f32 v73, v112, v113
	v_cvt_pk_bf16_f32 v74, v114, v115
	v_cvt_pk_bf16_f32 v75, v116, v117
	v_cvt_pk_bf16_f32 v76, v118, v119
	v_cvt_pk_bf16_f32 v77, v120, v121
	v_cvt_pk_bf16_f32 v78, v122, v123
	v_cvt_pk_bf16_f32 v79, v124, v125
	v_cvt_pk_bf16_f32 v80, v126, v127
	v_cvt_pk_bf16_f32 v81, v128, v129
	v_add3_u32 v102, v82, v196, s83
	ds_read_b64_tr_b16 v[82:83],v102 offset:0
	ds_read_b64_tr_b16 v[84:85],v102 offset:512
	ds_read_b64_tr_b16 v[86:87],v102 offset:1024
	ds_read_b64_tr_b16 v[88:89],v102 offset:1536
	ds_read_b64_tr_b16 v[90:91],v102 offset:2048
	ds_read_b64_tr_b16 v[92:93],v102 offset:2560
	ds_read_b64_tr_b16 v[94:95],v102 offset:3072
	ds_read_b64_tr_b16 v[96:97],v102 offset:3584
	s_waitcnt lgkmcnt(0)
	s_nop 0
	v_mfma_f32_32x32x16_bf16 v[50:65], v[66:69], v[82:85], v[50:65]
	ds_read_b64_tr_b16 v[82:83],v102 offset:4096
	ds_read_b64_tr_b16 v[84:85],v102 offset:4608
	v_mfma_f32_32x32x16_bf16 v[50:65], v[70:73], v[86:89], v[50:65]
	ds_read_b64_tr_b16 v[86:87],v102 offset:5120
	ds_read_b64_tr_b16 v[88:89],v102 offset:5632
	v_mfma_f32_32x32x16_bf16 v[50:65], v[74:77], v[90:93], v[50:65]
	ds_read_b64_tr_b16 v[90:91],v102 offset:6144
	ds_read_b64_tr_b16 v[92:93],v102 offset:6656
	ds_read_b64_tr_b16 v[98:99],v102 offset:7168
	ds_read_b64_tr_b16 v[100:101],v102 offset:7680
	s_waitcnt lgkmcnt(0)
	v_mfma_f32_32x32x16_bf16 v[50:65], v[78:81], v[94:97], v[50:65]
	v_mfma_f32_32x32x16_bf16 v[34:49], v[66:69], v[82:85], v[34:49]
	v_mfma_f32_32x32x16_bf16 v[34:49], v[70:73], v[86:89], v[34:49]
	v_mfma_f32_32x32x16_bf16 v[34:49], v[74:77], v[90:93], v[34:49]
	v_mfma_f32_32x32x16_bf16 v[34:49], v[78:81], v[98:101], v[34:49]
	v_add_u32_e32 v102, 0x2000, v102
	ds_read_b64_tr_b16 v[82:83],v102 offset:0
	ds_read_b64_tr_b16 v[84:85],v102 offset:512
	ds_read_b64_tr_b16 v[86:87],v102 offset:1024
	ds_read_b64_tr_b16 v[88:89],v102 offset:1536
	ds_read_b64_tr_b16 v[90:91],v102 offset:2048
	ds_read_b64_tr_b16 v[92:93],v102 offset:2560
	ds_read_b64_tr_b16 v[94:95],v102 offset:3072
	ds_read_b64_tr_b16 v[96:97],v102 offset:3584
	s_waitcnt lgkmcnt(0)
	s_nop 0
	v_mfma_f32_32x32x16_bf16 v[18:33], v[66:69], v[82:85], v[18:33]
	ds_read_b64_tr_b16 v[82:83],v102 offset:4096
	ds_read_b64_tr_b16 v[84:85],v102 offset:4608
	v_mfma_f32_32x32x16_bf16 v[18:33], v[70:73], v[86:89], v[18:33]
	ds_read_b64_tr_b16 v[86:87],v102 offset:5120
	ds_read_b64_tr_b16 v[88:89],v102 offset:5632
	v_mfma_f32_32x32x16_bf16 v[18:33], v[74:77], v[90:93], v[18:33]
	ds_read_b64_tr_b16 v[90:91],v102 offset:6144
	ds_read_b64_tr_b16 v[92:93],v102 offset:6656
	ds_read_b64_tr_b16 v[98:99],v102 offset:7168
	ds_read_b64_tr_b16 v[100:101],v102 offset:7680
	s_waitcnt lgkmcnt(0)
	v_mfma_f32_32x32x16_bf16 v[18:33], v[78:81], v[94:97], v[18:33]
	v_mfma_f32_32x32x16_bf16 v[2:17], v[66:69], v[82:85], v[2:17]
	v_mov_b32_e32 v66, v0
	s_nop 1
	v_permlane32_swap_b32_e32 v0, v66
	v_cmp_gt_u32_e32 vcc, 32, v193
	v_mfma_f32_32x32x16_bf16 v[2:17], v[70:73], v[86:89], v[2:17]
	v_mfma_f32_32x32x16_bf16 v[2:17], v[74:77], v[90:93], v[2:17]
	v_mfma_f32_32x32x16_bf16 v[2:17], v[78:81], v[98:101], v[2:17]
	s_and_saveexec_b64 s[6:7], vcc
	v_lshl_add_u32 v67, v185, 2, s8
	v_add_f32_e32 v0, v0, v66
	ds_write_b32 v67, v0 offset:128
	s_or_b64 exec, exec, s[6:7]
	s_waitcnt lgkmcnt(0)
	s_barrier
; __device__ __forceinline__ int crow(int r,int hi){return (r&3)+8*(r>>2)+4*hi;}
; __device__ __forceinline__ unsigned cvtpk_s(float lo,float hi){f32x2_t v={lo,hi};bf16x2_t b=__builtin_convertvector(v,bf16x2_t);return __builtin_bit_cast(unsigned,b);}
; template<int VH,bool HAS_BIAS,int MODE> __device__ __forceinline__ void attn_unit2(const bf16*Qb,int qp,const bf16*__restrict__ Kb,int kp,const bf16*__restrict__ Vb,int vp,bf16*Ob,int op,int q0,int NT,const float*relb,char*shm,float lam,const float*subg,float gmul){
;     ...
;   if(HAS_BIAS){ const float L2E=1.4426950408889634f; cb=L2E*relb[15*8]; ca=L2E*relb[31*8];
;     for(int i=tid;i<768;i+=512){ const int rel=i-384; const int n=rel<0?-rel:rel; int bk=n<8?n:(8+(31-__builtin_clz((unsigned)(n*n)))-6); if(n>=8&&bk>15)bk=15; if(rel>0)bk+=16; btab[i]=L2E*relb[bk*8]; } }
;     ...
;   float rli[16];
;   #pragma unroll
;   for(int r=0;r<16;++r)rli[r]=__builtin_amdgcn_rcpf(wsf[32+crow(r,hi)]);
;   bf16*Ow=Ob+(long)(q0+wid*QBLK)*op;
;   typedef __attribute__((address_space(3))) unsigned lds_u32;
;   lds_u32* park=(lds_u32*)((lds_ptr_)shm+LM::BYTES)+tid;
;   if(MODE==1){
;     #pragma unroll
;     for(int d0=0;d0<2*VH;++d0)
;       #pragma unroll
;       for(int r=0;r<16;r+=2)park[(d0*8+(r>>1))*512]=cvtpk_s(o[d0][r]*rli[r],o[d0][r+1]*rli[r+1]);
	v_lshl_add_u32 v0, v194, 2, s8
	ds_read_b128 v[66:69], v0 offset:128
	ds_read_b128 v[70:73], v0 offset:160
	s_waitcnt lgkmcnt(1)
	v_rcp_f32_e32 v74, v66
	v_rcp_f32_e32 v75, v67
	v_rcp_f32_e32 v76, v68
	v_rcp_f32_e32 v77, v69
	ds_read_b128 v[66:69], v0 offset:192
	s_waitcnt lgkmcnt(1)
	v_rcp_f32_e32 v78, v70
	v_rcp_f32_e32 v79, v71
	v_rcp_f32_e32 v80, v72
	v_rcp_f32_e32 v81, v73
	ds_read_b128 v[70:73], v0 offset:224
	v_pk_mul_f32 v[50:51], v[50:51], v[74:75]
	v_lshl_add_u32 v0, v184, 2, 0
	v_cvt_pk_bf16_f32 v82, v50, v51
	v_pk_mul_f32 v[50:51], v[52:53], v[76:77]
	s_waitcnt lgkmcnt(1)
	v_rcp_f32_e32 v66, v66
	v_rcp_f32_e32 v67, v67
	v_add_u32_e32 v0, 0x15400, v0
	v_cvt_pk_bf16_f32 v50, v50, v51
	v_rcp_f32_e32 v68, v68
	v_rcp_f32_e32 v69, v69
	ds_write2st64_b32 v0, v82, v50 offset1:8
	v_pk_mul_f32 v[50:51], v[54:55], v[78:79]
	s_waitcnt lgkmcnt(1)
	v_rcp_f32_e32 v70, v70
	v_cvt_pk_bf16_f32 v52, v50, v51
	v_pk_mul_f32 v[50:51], v[56:57], v[80:81]
	v_rcp_f32_e32 v71, v71
	v_cvt_pk_bf16_f32 v50, v50, v51
	v_rcp_f32_e32 v72, v72
	v_rcp_f32_e32 v73, v73
	ds_write2st64_b32 v0, v52, v50 offset0:16 offset1:24
	v_pk_mul_f32 v[50:51], v[58:59], v[66:67]
	v_pk_mul_f32 v[34:35], v[34:35], v[74:75]
	v_cvt_pk_bf16_f32 v52, v50, v51
	v_pk_mul_f32 v[50:51], v[60:61], v[68:69]
	v_pk_mul_f32 v[18:19], v[18:19], v[74:75]
	v_cvt_pk_bf16_f32 v50, v50, v51
	ds_write2st64_b32 v0, v52, v50 offset0:32 offset1:40
	v_pk_mul_f32 v[50:51], v[62:63], v[70:71]
	v_pk_mul_f32 v[2:3], v[2:3], v[74:75]
	v_cvt_pk_bf16_f32 v52, v50, v51
	v_pk_mul_f32 v[50:51], v[64:65], v[72:73]
	v_mov_b32_e32 v184, v182
	v_cvt_pk_bf16_f32 v50, v50, v51
	ds_write2st64_b32 v0, v52, v50 offset0:48 offset1:56
	v_cvt_pk_bf16_f32 v50, v34, v35
	v_pk_mul_f32 v[34:35], v[36:37], v[76:77]
	s_nop 0
	v_cvt_pk_bf16_f32 v34, v34, v35
	ds_write2st64_b32 v0, v50, v34 offset0:64 offset1:72
	v_pk_mul_f32 v[34:35], v[38:39], v[78:79]
	s_nop 0
	v_cvt_pk_bf16_f32 v36, v34, v35
	v_pk_mul_f32 v[34:35], v[40:41], v[80:81]
	s_nop 0
	v_cvt_pk_bf16_f32 v34, v34, v35
	ds_write2st64_b32 v0, v36, v34 offset0:80 offset1:88
	v_pk_mul_f32 v[34:35], v[42:43], v[66:67]
	s_nop 0
	v_cvt_pk_bf16_f32 v36, v34, v35
	v_pk_mul_f32 v[34:35], v[44:45], v[68:69]
	s_nop 0
	v_cvt_pk_bf16_f32 v34, v34, v35
	ds_write2st64_b32 v0, v36, v34 offset0:96 offset1:104
	v_pk_mul_f32 v[34:35], v[46:47], v[70:71]
	s_nop 0
	v_cvt_pk_bf16_f32 v36, v34, v35
	v_pk_mul_f32 v[34:35], v[48:49], v[72:73]
	s_nop 0
	v_cvt_pk_bf16_f32 v34, v34, v35
	ds_write2st64_b32 v0, v36, v34 offset0:112 offset1:120
	v_cvt_pk_bf16_f32 v34, v18, v19
	v_pk_mul_f32 v[18:19], v[20:21], v[76:77]
	s_nop 0
	v_cvt_pk_bf16_f32 v18, v18, v19
	ds_write2st64_b32 v0, v34, v18 offset0:128 offset1:136
	v_pk_mul_f32 v[18:19], v[22:23], v[78:79]
	s_nop 0
	v_cvt_pk_bf16_f32 v20, v18, v19
	v_pk_mul_f32 v[18:19], v[24:25], v[80:81]
	s_nop 0
	v_cvt_pk_bf16_f32 v18, v18, v19
	ds_write2st64_b32 v0, v20, v18 offset0:144 offset1:152
	v_pk_mul_f32 v[18:19], v[26:27], v[66:67]
	s_nop 0
	v_cvt_pk_bf16_f32 v20, v18, v19
	v_pk_mul_f32 v[18:19], v[28:29], v[68:69]
	s_nop 0
	v_cvt_pk_bf16_f32 v18, v18, v19
	ds_write2st64_b32 v0, v20, v18 offset0:160 offset1:168
	v_pk_mul_f32 v[18:19], v[30:31], v[70:71]
	s_nop 0
	v_cvt_pk_bf16_f32 v20, v18, v19
	v_pk_mul_f32 v[18:19], v[32:33], v[72:73]
	s_nop 0
	v_cvt_pk_bf16_f32 v18, v18, v19
	ds_write2st64_b32 v0, v20, v18 offset0:176 offset1:184
	v_cvt_pk_bf16_f32 v18, v2, v3
	v_pk_mul_f32 v[2:3], v[4:5], v[76:77]
	s_nop 0
	v_cvt_pk_bf16_f32 v2, v2, v3
	ds_write2st64_b32 v0, v18, v2 offset0:192 offset1:200
	v_pk_mul_f32 v[2:3], v[6:7], v[78:79]
	s_nop 0
	v_cvt_pk_bf16_f32 v4, v2, v3
	v_pk_mul_f32 v[2:3], v[8:9], v[80:81]
	s_nop 0
	v_cvt_pk_bf16_f32 v2, v2, v3
	ds_write2st64_b32 v0, v4, v2 offset0:208 offset1:216
	v_pk_mul_f32 v[2:3], v[10:11], v[66:67]
	s_nop 0
	v_cvt_pk_bf16_f32 v4, v2, v3
	v_pk_mul_f32 v[2:3], v[12:13], v[68:69]
	s_nop 0
	v_cvt_pk_bf16_f32 v2, v2, v3
	ds_write2st64_b32 v0, v4, v2 offset0:224 offset1:232
	v_pk_mul_f32 v[2:3], v[14:15], v[70:71]
	s_nop 0
	v_cvt_pk_bf16_f32 v4, v2, v3
	v_pk_mul_f32 v[2:3], v[16:17], v[72:73]
	s_nop 0
	v_cvt_pk_bf16_f32 v2, v2, v3
	ds_write2st64_b32 v0, v4, v2 offset0:240 offset1:248
	s_waitcnt lgkmcnt(0)
	s_barrier
	s_load_dwordx2 s[42:43], s[0:1], 0xb8
	global_load_dword v0, v1, s[40:41] offset:480
	global_load_dword v34, v1, s[40:41] offset:992
	v_readfirstlane_b32 s81, v184
	v_cmp_gt_i32_e32 vcc, s64, v184
	s_and_saveexec_b64 s[54:55], vcc
	s_branch .LBB0_1153
	v_max_i32_e32 v2, 0x100, v184
	v_sub_u32_e32 v2, v2, v184
	v_add_u32_e32 v3, 0x1ff, v2
	v_cmp_lt_u32_e32 vcc, s63, v3
	s_mov_b64 s[6:7], -1
	v_mov_b32_e32 v2, v184
	s_and_saveexec_b64 s[56:57], vcc
	s_cbranch_execz .LBB0_1150
	v_lshrrev_b32_e32 v4, 9, v3
	v_add_u32_e32 v185, 0x200, v184
	v_add_u32_e32 v5, -1, v4
	v_cmp_lt_u32_e32 vcc, 1, v5
	v_mov_b32_e32 v6, 0
	v_mov_b64_e32 v[2:3], v[184:185]
	s_and_saveexec_b64 s[58:59], vcc
	s_cbranch_execz .LBB0_1147
	v_lshrrev_b32_e32 v2, 1, v5
	v_add_u32_e32 v2, 1, v2
	v_and_b32_e32 v6, -2, v2
	v_lshl_add_u32 v7, v184, 2, s65
	s_mov_b32 s33, 0
	s_mov_b64 s[60:61], 0
	v_mov_b64_e32 v[2:3], v[184:185]
